# w_in epilogue: GELU and sigmoid column tiles with folded constants (x*(c1+c2*x^2) in the exponent) and packed f32 mul/fma/add (about 7 VALU slots per element instead of 11)
# baseline (speedup 1.0000x reference)
.Lwin_c_done:
	s_lshl_b32 s60, s60, 9
	s_add_u32 s56, s56, s61
	s_addc_u32 s57, s57, 0
	s_add_u32 s56, s56, s60
	s_addc_u32 s57, s57, 0
	s_lshl_b32 s60, s14, 8
	s_lshl_b32 s60, s60, s13
	s_add_u32 s60, s56, s60
	s_addc_u32 s61, s57, 0
	s_mov_b32 s64, 16
	s_lshl_b32 s64, s64, s13
	s_lshl_b32 s65, s64, 2
	v_lshlrev_b32_e32 v174, s13, v149
	v_lshl_add_u32 v174, v146, 1, v174
	s_mov_b32 s98, 0xbdd2d3e8
	s_mov_b32 s99, 0xbdd2d3e8
	s_mov_b32 s100, 0xbfb8aa3b
	s_mov_b32 s101, 0xbfb8aa3b
	v_mov_b32_e32 v250, 0xc0135761
	v_mov_b32_e32 v251, 0xc0135761
	v_mov_b32_e32 v252, 1.0
	v_mov_b32_e32 v253, 1.0
	s_cmp_eq_u32 s16, 1
	s_cbranch_scc1 .Lwin_act1
	s_cmp_eq_u32 s16, 2
	s_cbranch_scc1 .Lwin_act2
	v_cvt_pk_bf16_f32 v128, v124, v125
	v_cvt_pk_bf16_f32 v129, v126, v127
	v_cvt_pk_bf16_f32 v130, v120, v121
	v_cvt_pk_bf16_f32 v131, v122, v123
	global_store_dwordx4 v174, v[128:131], s[60:61]
	v_cvt_pk_bf16_f32 v120, v116, v117
	v_cvt_pk_bf16_f32 v121, v118, v119
	v_cvt_pk_bf16_f32 v122, v112, v113
	v_cvt_pk_bf16_f32 v123, v114, v115
	global_store_dwordx4 v174, v[120:123], s[60:61] offset:256
	s_add_u32 s60, s60, s64
	s_addc_u32 s61, s61, 0
	v_cvt_pk_bf16_f32 v112, v108, v109
	v_cvt_pk_bf16_f32 v113, v110, v111
	v_cvt_pk_bf16_f32 v114, v104, v105
	v_cvt_pk_bf16_f32 v115, v106, v107
	global_store_dwordx4 v174, v[112:115], s[60:61]
	v_cvt_pk_bf16_f32 v104, v100, v101
	v_cvt_pk_bf16_f32 v105, v102, v103
	v_cvt_pk_bf16_f32 v106, v96, v97
	v_cvt_pk_bf16_f32 v107, v98, v99
	global_store_dwordx4 v174, v[104:107], s[60:61] offset:256
	s_add_u32 s60, s60, s64
	s_addc_u32 s61, s61, 0
	v_cvt_pk_bf16_f32 v96, v92, v93
	v_cvt_pk_bf16_f32 v97, v94, v95
	v_cvt_pk_bf16_f32 v98, v88, v89
	v_cvt_pk_bf16_f32 v99, v90, v91
	global_store_dwordx4 v174, v[96:99], s[60:61]
	v_cvt_pk_bf16_f32 v88, v84, v85
	v_cvt_pk_bf16_f32 v89, v86, v87
	v_cvt_pk_bf16_f32 v90, v80, v81
	v_cvt_pk_bf16_f32 v91, v82, v83
	global_store_dwordx4 v174, v[88:91], s[60:61] offset:256
	s_add_u32 s60, s60, s64
	s_addc_u32 s61, s61, 0
	v_cvt_pk_bf16_f32 v80, v76, v77
	v_cvt_pk_bf16_f32 v81, v78, v79
	v_cvt_pk_bf16_f32 v82, v72, v73
	v_cvt_pk_bf16_f32 v83, v74, v75
	global_store_dwordx4 v174, v[80:83], s[60:61]
	v_cvt_pk_bf16_f32 v72, v68, v69
	v_cvt_pk_bf16_f32 v73, v70, v71
	v_cvt_pk_bf16_f32 v74, v64, v65
	v_cvt_pk_bf16_f32 v75, v66, v67
	global_store_dwordx4 v174, v[72:75], s[60:61] offset:256
	s_add_u32 s60, s60, s64
	s_addc_u32 s61, s61, 0
	s_add_u32 s60, s60, s65
	s_addc_u32 s61, s61, 0
	v_cvt_pk_bf16_f32 v64, v60, v61
	v_cvt_pk_bf16_f32 v65, v62, v63
	v_cvt_pk_bf16_f32 v66, v56, v57
	v_cvt_pk_bf16_f32 v67, v58, v59
	global_store_dwordx4 v174, v[64:67], s[60:61]
	v_cvt_pk_bf16_f32 v56, v52, v53
	v_cvt_pk_bf16_f32 v57, v54, v55
	v_cvt_pk_bf16_f32 v58, v48, v49
	v_cvt_pk_bf16_f32 v59, v50, v51
	global_store_dwordx4 v174, v[56:59], s[60:61] offset:256
	s_add_u32 s60, s60, s64
	s_addc_u32 s61, s61, 0
	v_cvt_pk_bf16_f32 v48, v44, v45
	v_cvt_pk_bf16_f32 v49, v46, v47
	v_cvt_pk_bf16_f32 v50, v40, v41
	v_cvt_pk_bf16_f32 v51, v42, v43
	global_store_dwordx4 v174, v[48:51], s[60:61]
	v_cvt_pk_bf16_f32 v40, v36, v37
	v_cvt_pk_bf16_f32 v41, v38, v39
	v_cvt_pk_bf16_f32 v42, v32, v33
	v_cvt_pk_bf16_f32 v43, v34, v35
	global_store_dwordx4 v174, v[40:43], s[60:61] offset:256
	s_add_u32 s60, s60, s64
	s_addc_u32 s61, s61, 0
	v_cvt_pk_bf16_f32 v32, v28, v29
	v_cvt_pk_bf16_f32 v33, v30, v31
	v_cvt_pk_bf16_f32 v34, v24, v25
	v_cvt_pk_bf16_f32 v35, v26, v27
	global_store_dwordx4 v174, v[32:35], s[60:61]
	v_cvt_pk_bf16_f32 v24, v20, v21
	v_cvt_pk_bf16_f32 v25, v22, v23
	v_cvt_pk_bf16_f32 v26, v16, v17
	v_cvt_pk_bf16_f32 v27, v18, v19
	global_store_dwordx4 v174, v[24:27], s[60:61] offset:256
	s_add_u32 s60, s60, s64
	s_addc_u32 s61, s61, 0
	v_cvt_pk_bf16_f32 v16, v12, v13
	v_cvt_pk_bf16_f32 v17, v14, v15
	v_cvt_pk_bf16_f32 v18, v8, v9
	v_cvt_pk_bf16_f32 v19, v10, v11
	global_store_dwordx4 v174, v[16:19], s[60:61]
	v_cvt_pk_bf16_f32 v8, v4, v5
	v_cvt_pk_bf16_f32 v9, v6, v7
	v_cvt_pk_bf16_f32 v10, v0, v1
	v_cvt_pk_bf16_f32 v11, v2, v3
	global_store_dwordx4 v174, v[8:11], s[60:61] offset:256
	s_branch .Lwin_done
.Lwin_act1:
	v_pk_mul_f32 v[128:129], v[124:125], v[124:125]
	v_pk_mul_f32 v[130:131], v[126:127], v[126:127]
	v_pk_mul_f32 v[132:133], v[120:121], v[120:121]
	v_pk_mul_f32 v[134:135], v[122:123], v[122:123]
	v_pk_fma_f32 v[128:129], v[128:129], s[98:99], v[250:251]
	v_pk_fma_f32 v[130:131], v[130:131], s[98:99], v[250:251]
	v_pk_fma_f32 v[132:133], v[132:133], s[98:99], v[250:251]
	v_pk_fma_f32 v[134:135], v[134:135], s[98:99], v[250:251]
	v_pk_mul_f32 v[128:129], v[124:125], v[128:129]
	v_pk_mul_f32 v[130:131], v[126:127], v[130:131]
	v_pk_mul_f32 v[132:133], v[120:121], v[132:133]
	v_pk_mul_f32 v[134:135], v[122:123], v[134:135]
	v_exp_f32_e32 v128, v128
	v_exp_f32_e32 v129, v129
	v_exp_f32_e32 v130, v130
	v_exp_f32_e32 v131, v131
	v_exp_f32_e32 v132, v132
	v_exp_f32_e32 v133, v133
	v_exp_f32_e32 v134, v134
	v_exp_f32_e32 v135, v135
	v_pk_add_f32 v[128:129], v[128:129], v[252:253]
	v_pk_add_f32 v[130:131], v[130:131], v[252:253]
	v_pk_add_f32 v[132:133], v[132:133], v[252:253]
	v_pk_add_f32 v[134:135], v[134:135], v[252:253]
	v_rcp_f32_e32 v128, v128
	v_rcp_f32_e32 v129, v129
	v_rcp_f32_e32 v130, v130
	v_rcp_f32_e32 v131, v131
	v_rcp_f32_e32 v132, v132
	v_rcp_f32_e32 v133, v133
	v_rcp_f32_e32 v134, v134
	v_rcp_f32_e32 v135, v135
	v_pk_mul_f32 v[128:129], v[124:125], v[128:129]
	v_pk_mul_f32 v[130:131], v[126:127], v[130:131]
	v_pk_mul_f32 v[132:133], v[120:121], v[132:133]
	v_pk_mul_f32 v[134:135], v[122:123], v[134:135]
	v_cvt_pk_bf16_f32 v128, v128, v129
	v_cvt_pk_bf16_f32 v129, v130, v131
	v_cvt_pk_bf16_f32 v130, v132, v133
	v_cvt_pk_bf16_f32 v131, v134, v135
	global_store_dwordx4 v174, v[128:131], s[60:61]
	v_pk_mul_f32 v[120:121], v[116:117], v[116:117]
	v_pk_mul_f32 v[122:123], v[118:119], v[118:119]
	v_pk_mul_f32 v[124:125], v[112:113], v[112:113]
	v_pk_mul_f32 v[126:127], v[114:115], v[114:115]
	v_pk_fma_f32 v[120:121], v[120:121], s[98:99], v[250:251]
	v_pk_fma_f32 v[122:123], v[122:123], s[98:99], v[250:251]
	v_pk_fma_f32 v[124:125], v[124:125], s[98:99], v[250:251]
	v_pk_fma_f32 v[126:127], v[126:127], s[98:99], v[250:251]
	v_pk_mul_f32 v[120:121], v[116:117], v[120:121]
	v_pk_mul_f32 v[122:123], v[118:119], v[122:123]
	v_pk_mul_f32 v[124:125], v[112:113], v[124:125]
	v_pk_mul_f32 v[126:127], v[114:115], v[126:127]
	v_exp_f32_e32 v120, v120
	v_exp_f32_e32 v121, v121
	v_exp_f32_e32 v122, v122
	v_exp_f32_e32 v123, v123
	v_exp_f32_e32 v124, v124
	v_exp_f32_e32 v125, v125
	v_exp_f32_e32 v126, v126
	v_exp_f32_e32 v127, v127
	v_pk_add_f32 v[120:121], v[120:121], v[252:253]
	v_pk_add_f32 v[122:123], v[122:123], v[252:253]
	v_pk_add_f32 v[124:125], v[124:125], v[252:253]
	v_pk_add_f32 v[126:127], v[126:127], v[252:253]
	v_rcp_f32_e32 v120, v120
	v_rcp_f32_e32 v121, v121
	v_rcp_f32_e32 v122, v122
	v_rcp_f32_e32 v123, v123
	v_rcp_f32_e32 v124, v124
	v_rcp_f32_e32 v125, v125
	v_rcp_f32_e32 v126, v126
	v_rcp_f32_e32 v127, v127
	v_pk_mul_f32 v[120:121], v[116:117], v[120:121]
	v_pk_mul_f32 v[122:123], v[118:119], v[122:123]
	v_pk_mul_f32 v[124:125], v[112:113], v[124:125]
	v_pk_mul_f32 v[126:127], v[114:115], v[126:127]
	v_cvt_pk_bf16_f32 v120, v120, v121
	v_cvt_pk_bf16_f32 v121, v122, v123
	v_cvt_pk_bf16_f32 v122, v124, v125
	v_cvt_pk_bf16_f32 v123, v126, v127
	global_store_dwordx4 v174, v[120:123], s[60:61] offset:256
	s_add_u32 s60, s60, s64
	s_addc_u32 s61, s61, 0
	v_pk_mul_f32 v[112:113], v[108:109], v[108:109]
	v_pk_mul_f32 v[114:115], v[110:111], v[110:111]
	v_pk_mul_f32 v[116:117], v[104:105], v[104:105]
	v_pk_mul_f32 v[118:119], v[106:107], v[106:107]
	v_pk_fma_f32 v[112:113], v[112:113], s[98:99], v[250:251]
	v_pk_fma_f32 v[114:115], v[114:115], s[98:99], v[250:251]
	v_pk_fma_f32 v[116:117], v[116:117], s[98:99], v[250:251]
	v_pk_fma_f32 v[118:119], v[118:119], s[98:99], v[250:251]
	v_pk_mul_f32 v[112:113], v[108:109], v[112:113]
	v_pk_mul_f32 v[114:115], v[110:111], v[114:115]
	v_pk_mul_f32 v[116:117], v[104:105], v[116:117]
	v_pk_mul_f32 v[118:119], v[106:107], v[118:119]
	v_exp_f32_e32 v112, v112
	v_exp_f32_e32 v113, v113
	v_exp_f32_e32 v114, v114
	v_exp_f32_e32 v115, v115
	v_exp_f32_e32 v116, v116
	v_exp_f32_e32 v117, v117
	v_exp_f32_e32 v118, v118
	v_exp_f32_e32 v119, v119
	v_pk_add_f32 v[112:113], v[112:113], v[252:253]
	v_pk_add_f32 v[114:115], v[114:115], v[252:253]
	v_pk_add_f32 v[116:117], v[116:117], v[252:253]
	v_pk_add_f32 v[118:119], v[118:119], v[252:253]
	v_rcp_f32_e32 v112, v112
	v_rcp_f32_e32 v113, v113
	v_rcp_f32_e32 v114, v114
	v_rcp_f32_e32 v115, v115
	v_rcp_f32_e32 v116, v116
	v_rcp_f32_e32 v117, v117
	v_rcp_f32_e32 v118, v118
	v_rcp_f32_e32 v119, v119
	v_pk_mul_f32 v[112:113], v[108:109], v[112:113]
	v_pk_mul_f32 v[114:115], v[110:111], v[114:115]
	v_pk_mul_f32 v[116:117], v[104:105], v[116:117]
	v_pk_mul_f32 v[118:119], v[106:107], v[118:119]
	v_cvt_pk_bf16_f32 v112, v112, v113
	v_cvt_pk_bf16_f32 v113, v114, v115
	v_cvt_pk_bf16_f32 v114, v116, v117
	v_cvt_pk_bf16_f32 v115, v118, v119
	global_store_dwordx4 v174, v[112:115], s[60:61]
	v_pk_mul_f32 v[104:105], v[100:101], v[100:101]
	v_pk_mul_f32 v[106:107], v[102:103], v[102:103]
	v_pk_mul_f32 v[108:109], v[96:97], v[96:97]
	v_pk_mul_f32 v[110:111], v[98:99], v[98:99]
	v_pk_fma_f32 v[104:105], v[104:105], s[98:99], v[250:251]
	v_pk_fma_f32 v[106:107], v[106:107], s[98:99], v[250:251]
	v_pk_fma_f32 v[108:109], v[108:109], s[98:99], v[250:251]
	v_pk_fma_f32 v[110:111], v[110:111], s[98:99], v[250:251]
	v_pk_mul_f32 v[104:105], v[100:101], v[104:105]
	v_pk_mul_f32 v[106:107], v[102:103], v[106:107]
	v_pk_mul_f32 v[108:109], v[96:97], v[108:109]
	v_pk_mul_f32 v[110:111], v[98:99], v[110:111]
	v_exp_f32_e32 v104, v104
	v_exp_f32_e32 v105, v105
	v_exp_f32_e32 v106, v106
	v_exp_f32_e32 v107, v107
	v_exp_f32_e32 v108, v108
	v_exp_f32_e32 v109, v109
	v_exp_f32_e32 v110, v110
	v_exp_f32_e32 v111, v111
	v_pk_add_f32 v[104:105], v[104:105], v[252:253]
	v_pk_add_f32 v[106:107], v[106:107], v[252:253]
	v_pk_add_f32 v[108:109], v[108:109], v[252:253]
	v_pk_add_f32 v[110:111], v[110:111], v[252:253]
	v_rcp_f32_e32 v104, v104
	v_rcp_f32_e32 v105, v105
	v_rcp_f32_e32 v106, v106
	v_rcp_f32_e32 v107, v107
	v_rcp_f32_e32 v108, v108
	v_rcp_f32_e32 v109, v109
	v_rcp_f32_e32 v110, v110
	v_rcp_f32_e32 v111, v111
	v_pk_mul_f32 v[104:105], v[100:101], v[104:105]
	v_pk_mul_f32 v[106:107], v[102:103], v[106:107]
	v_pk_mul_f32 v[108:109], v[96:97], v[108:109]
	v_pk_mul_f32 v[110:111], v[98:99], v[110:111]
	v_cvt_pk_bf16_f32 v104, v104, v105
	v_cvt_pk_bf16_f32 v105, v106, v107
	v_cvt_pk_bf16_f32 v106, v108, v109
	v_cvt_pk_bf16_f32 v107, v110, v111
	global_store_dwordx4 v174, v[104:107], s[60:61] offset:256
	s_add_u32 s60, s60, s64
	s_addc_u32 s61, s61, 0
	v_pk_mul_f32 v[96:97], v[92:93], v[92:93]
	v_pk_mul_f32 v[98:99], v[94:95], v[94:95]
	v_pk_mul_f32 v[100:101], v[88:89], v[88:89]
	v_pk_mul_f32 v[102:103], v[90:91], v[90:91]
	v_pk_fma_f32 v[96:97], v[96:97], s[98:99], v[250:251]
	v_pk_fma_f32 v[98:99], v[98:99], s[98:99], v[250:251]
	v_pk_fma_f32 v[100:101], v[100:101], s[98:99], v[250:251]
	v_pk_fma_f32 v[102:103], v[102:103], s[98:99], v[250:251]
	v_pk_mul_f32 v[96:97], v[92:93], v[96:97]
	v_pk_mul_f32 v[98:99], v[94:95], v[98:99]
	v_pk_mul_f32 v[100:101], v[88:89], v[100:101]
	v_pk_mul_f32 v[102:103], v[90:91], v[102:103]
	v_exp_f32_e32 v96, v96
	v_exp_f32_e32 v97, v97
	v_exp_f32_e32 v98, v98
	v_exp_f32_e32 v99, v99
	v_exp_f32_e32 v100, v100
	v_exp_f32_e32 v101, v101
	v_exp_f32_e32 v102, v102
	v_exp_f32_e32 v103, v103
	v_pk_add_f32 v[96:97], v[96:97], v[252:253]
	v_pk_add_f32 v[98:99], v[98:99], v[252:253]
	v_pk_add_f32 v[100:101], v[100:101], v[252:253]
	v_pk_add_f32 v[102:103], v[102:103], v[252:253]
	v_rcp_f32_e32 v96, v96
	v_rcp_f32_e32 v97, v97
	v_rcp_f32_e32 v98, v98
	v_rcp_f32_e32 v99, v99
	v_rcp_f32_e32 v100, v100
	v_rcp_f32_e32 v101, v101
	v_rcp_f32_e32 v102, v102
	v_rcp_f32_e32 v103, v103
	v_pk_mul_f32 v[96:97], v[92:93], v[96:97]
	v_pk_mul_f32 v[98:99], v[94:95], v[98:99]
	v_pk_mul_f32 v[100:101], v[88:89], v[100:101]
	v_pk_mul_f32 v[102:103], v[90:91], v[102:103]
	v_cvt_pk_bf16_f32 v96, v96, v97
	v_cvt_pk_bf16_f32 v97, v98, v99
	v_cvt_pk_bf16_f32 v98, v100, v101
	v_cvt_pk_bf16_f32 v99, v102, v103
	global_store_dwordx4 v174, v[96:99], s[60:61]
	v_pk_mul_f32 v[88:89], v[84:85], v[84:85]
	v_pk_mul_f32 v[90:91], v[86:87], v[86:87]
	v_pk_mul_f32 v[92:93], v[80:81], v[80:81]
	v_pk_mul_f32 v[94:95], v[82:83], v[82:83]
	v_pk_fma_f32 v[88:89], v[88:89], s[98:99], v[250:251]
	v_pk_fma_f32 v[90:91], v[90:91], s[98:99], v[250:251]
	v_pk_fma_f32 v[92:93], v[92:93], s[98:99], v[250:251]
	v_pk_fma_f32 v[94:95], v[94:95], s[98:99], v[250:251]
	v_pk_mul_f32 v[88:89], v[84:85], v[88:89]
	v_pk_mul_f32 v[90:91], v[86:87], v[90:91]
	v_pk_mul_f32 v[92:93], v[80:81], v[92:93]
	v_pk_mul_f32 v[94:95], v[82:83], v[94:95]
	v_exp_f32_e32 v88, v88
	v_exp_f32_e32 v89, v89
	v_exp_f32_e32 v90, v90
	v_exp_f32_e32 v91, v91
	v_exp_f32_e32 v92, v92
	v_exp_f32_e32 v93, v93
	v_exp_f32_e32 v94, v94
	v_exp_f32_e32 v95, v95
	v_pk_add_f32 v[88:89], v[88:89], v[252:253]
	v_pk_add_f32 v[90:91], v[90:91], v[252:253]
	v_pk_add_f32 v[92:93], v[92:93], v[252:253]
	v_pk_add_f32 v[94:95], v[94:95], v[252:253]
	v_rcp_f32_e32 v88, v88
	v_rcp_f32_e32 v89, v89
	v_rcp_f32_e32 v90, v90
	v_rcp_f32_e32 v91, v91
	v_rcp_f32_e32 v92, v92
	v_rcp_f32_e32 v93, v93
	v_rcp_f32_e32 v94, v94
	v_rcp_f32_e32 v95, v95
	v_pk_mul_f32 v[88:89], v[84:85], v[88:89]
	v_pk_mul_f32 v[90:91], v[86:87], v[90:91]
	v_pk_mul_f32 v[92:93], v[80:81], v[92:93]
	v_pk_mul_f32 v[94:95], v[82:83], v[94:95]
	v_cvt_pk_bf16_f32 v88, v88, v89
	v_cvt_pk_bf16_f32 v89, v90, v91
	v_cvt_pk_bf16_f32 v90, v92, v93
	v_cvt_pk_bf16_f32 v91, v94, v95
	global_store_dwordx4 v174, v[88:91], s[60:61] offset:256
	s_add_u32 s60, s60, s64
	s_addc_u32 s61, s61, 0
	v_pk_mul_f32 v[80:81], v[76:77], v[76:77]
	v_pk_mul_f32 v[82:83], v[78:79], v[78:79]
	v_pk_mul_f32 v[84:85], v[72:73], v[72:73]
	v_pk_mul_f32 v[86:87], v[74:75], v[74:75]
	v_pk_fma_f32 v[80:81], v[80:81], s[98:99], v[250:251]
	v_pk_fma_f32 v[82:83], v[82:83], s[98:99], v[250:251]
	v_pk_fma_f32 v[84:85], v[84:85], s[98:99], v[250:251]
	v_pk_fma_f32 v[86:87], v[86:87], s[98:99], v[250:251]
	v_pk_mul_f32 v[80:81], v[76:77], v[80:81]
	v_pk_mul_f32 v[82:83], v[78:79], v[82:83]
	v_pk_mul_f32 v[84:85], v[72:73], v[84:85]
	v_pk_mul_f32 v[86:87], v[74:75], v[86:87]
	v_exp_f32_e32 v80, v80
	v_exp_f32_e32 v81, v81
	v_exp_f32_e32 v82, v82
	v_exp_f32_e32 v83, v83
	v_exp_f32_e32 v84, v84
	v_exp_f32_e32 v85, v85
	v_exp_f32_e32 v86, v86
	v_exp_f32_e32 v87, v87
	v_pk_add_f32 v[80:81], v[80:81], v[252:253]
	v_pk_add_f32 v[82:83], v[82:83], v[252:253]
	v_pk_add_f32 v[84:85], v[84:85], v[252:253]
	v_pk_add_f32 v[86:87], v[86:87], v[252:253]
	v_rcp_f32_e32 v80, v80
	v_rcp_f32_e32 v81, v81
	v_rcp_f32_e32 v82, v82
	v_rcp_f32_e32 v83, v83
	v_rcp_f32_e32 v84, v84
	v_rcp_f32_e32 v85, v85
	v_rcp_f32_e32 v86, v86
	v_rcp_f32_e32 v87, v87
	v_pk_mul_f32 v[80:81], v[76:77], v[80:81]
	v_pk_mul_f32 v[82:83], v[78:79], v[82:83]
	v_pk_mul_f32 v[84:85], v[72:73], v[84:85]
	v_pk_mul_f32 v[86:87], v[74:75], v[86:87]
	v_cvt_pk_bf16_f32 v80, v80, v81
	v_cvt_pk_bf16_f32 v81, v82, v83
	v_cvt_pk_bf16_f32 v82, v84, v85
	v_cvt_pk_bf16_f32 v83, v86, v87
	global_store_dwordx4 v174, v[80:83], s[60:61]
	v_pk_mul_f32 v[72:73], v[68:69], v[68:69]
	v_pk_mul_f32 v[74:75], v[70:71], v[70:71]
	v_pk_mul_f32 v[76:77], v[64:65], v[64:65]
	v_pk_mul_f32 v[78:79], v[66:67], v[66:67]
	v_pk_fma_f32 v[72:73], v[72:73], s[98:99], v[250:251]
	v_pk_fma_f32 v[74:75], v[74:75], s[98:99], v[250:251]
	v_pk_fma_f32 v[76:77], v[76:77], s[98:99], v[250:251]
	v_pk_fma_f32 v[78:79], v[78:79], s[98:99], v[250:251]
	v_pk_mul_f32 v[72:73], v[68:69], v[72:73]
	v_pk_mul_f32 v[74:75], v[70:71], v[74:75]
	v_pk_mul_f32 v[76:77], v[64:65], v[76:77]
	v_pk_mul_f32 v[78:79], v[66:67], v[78:79]
	v_exp_f32_e32 v72, v72
	v_exp_f32_e32 v73, v73
	v_exp_f32_e32 v74, v74
	v_exp_f32_e32 v75, v75
	v_exp_f32_e32 v76, v76
	v_exp_f32_e32 v77, v77
	v_exp_f32_e32 v78, v78
	v_exp_f32_e32 v79, v79
	v_pk_add_f32 v[72:73], v[72:73], v[252:253]
	v_pk_add_f32 v[74:75], v[74:75], v[252:253]
	v_pk_add_f32 v[76:77], v[76:77], v[252:253]
	v_pk_add_f32 v[78:79], v[78:79], v[252:253]
	v_rcp_f32_e32 v72, v72
	v_rcp_f32_e32 v73, v73
	v_rcp_f32_e32 v74, v74
	v_rcp_f32_e32 v75, v75
	v_rcp_f32_e32 v76, v76
	v_rcp_f32_e32 v77, v77
	v_rcp_f32_e32 v78, v78
	v_rcp_f32_e32 v79, v79
	v_pk_mul_f32 v[72:73], v[68:69], v[72:73]
	v_pk_mul_f32 v[74:75], v[70:71], v[74:75]
	v_pk_mul_f32 v[76:77], v[64:65], v[76:77]
	v_pk_mul_f32 v[78:79], v[66:67], v[78:79]
	v_cvt_pk_bf16_f32 v72, v72, v73
	v_cvt_pk_bf16_f32 v73, v74, v75
	v_cvt_pk_bf16_f32 v74, v76, v77
	v_cvt_pk_bf16_f32 v75, v78, v79
	global_store_dwordx4 v174, v[72:75], s[60:61] offset:256
	s_add_u32 s60, s60, s64
	s_addc_u32 s61, s61, 0
	s_add_u32 s60, s60, s65
	s_addc_u32 s61, s61, 0
	v_pk_mul_f32 v[64:65], v[60:61], v[60:61]
	v_pk_mul_f32 v[66:67], v[62:63], v[62:63]
	v_pk_mul_f32 v[68:69], v[56:57], v[56:57]
	v_pk_mul_f32 v[70:71], v[58:59], v[58:59]
	v_pk_fma_f32 v[64:65], v[64:65], s[98:99], v[250:251]
	v_pk_fma_f32 v[66:67], v[66:67], s[98:99], v[250:251]
	v_pk_fma_f32 v[68:69], v[68:69], s[98:99], v[250:251]
	v_pk_fma_f32 v[70:71], v[70:71], s[98:99], v[250:251]
	v_pk_mul_f32 v[64:65], v[60:61], v[64:65]
	v_pk_mul_f32 v[66:67], v[62:63], v[66:67]
	v_pk_mul_f32 v[68:69], v[56:57], v[68:69]
	v_pk_mul_f32 v[70:71], v[58:59], v[70:71]
	v_exp_f32_e32 v64, v64
	v_exp_f32_e32 v65, v65
	v_exp_f32_e32 v66, v66
	v_exp_f32_e32 v67, v67
	v_exp_f32_e32 v68, v68
	v_exp_f32_e32 v69, v69
	v_exp_f32_e32 v70, v70
	v_exp_f32_e32 v71, v71
	v_pk_add_f32 v[64:65], v[64:65], v[252:253]
	v_pk_add_f32 v[66:67], v[66:67], v[252:253]
	v_pk_add_f32 v[68:69], v[68:69], v[252:253]
	v_pk_add_f32 v[70:71], v[70:71], v[252:253]
	v_rcp_f32_e32 v64, v64
	v_rcp_f32_e32 v65, v65
	v_rcp_f32_e32 v66, v66
	v_rcp_f32_e32 v67, v67
	v_rcp_f32_e32 v68, v68
	v_rcp_f32_e32 v69, v69
	v_rcp_f32_e32 v70, v70
	v_rcp_f32_e32 v71, v71
	v_pk_mul_f32 v[64:65], v[60:61], v[64:65]
	v_pk_mul_f32 v[66:67], v[62:63], v[66:67]
	v_pk_mul_f32 v[68:69], v[56:57], v[68:69]
	v_pk_mul_f32 v[70:71], v[58:59], v[70:71]
	v_cvt_pk_bf16_f32 v64, v64, v65
	v_cvt_pk_bf16_f32 v65, v66, v67
	v_cvt_pk_bf16_f32 v66, v68, v69
	v_cvt_pk_bf16_f32 v67, v70, v71
	global_store_dwordx4 v174, v[64:67], s[60:61]
	v_pk_mul_f32 v[56:57], v[52:53], v[52:53]
	v_pk_mul_f32 v[58:59], v[54:55], v[54:55]
	v_pk_mul_f32 v[60:61], v[48:49], v[48:49]
	v_pk_mul_f32 v[62:63], v[50:51], v[50:51]
	v_pk_fma_f32 v[56:57], v[56:57], s[98:99], v[250:251]
	v_pk_fma_f32 v[58:59], v[58:59], s[98:99], v[250:251]
	v_pk_fma_f32 v[60:61], v[60:61], s[98:99], v[250:251]
	v_pk_fma_f32 v[62:63], v[62:63], s[98:99], v[250:251]
	v_pk_mul_f32 v[56:57], v[52:53], v[56:57]
	v_pk_mul_f32 v[58:59], v[54:55], v[58:59]
	v_pk_mul_f32 v[60:61], v[48:49], v[60:61]
	v_pk_mul_f32 v[62:63], v[50:51], v[62:63]
	v_exp_f32_e32 v56, v56
	v_exp_f32_e32 v57, v57
	v_exp_f32_e32 v58, v58
	v_exp_f32_e32 v59, v59
	v_exp_f32_e32 v60, v60
	v_exp_f32_e32 v61, v61
	v_exp_f32_e32 v62, v62
	v_exp_f32_e32 v63, v63
	v_pk_add_f32 v[56:57], v[56:57], v[252:253]
	v_pk_add_f32 v[58:59], v[58:59], v[252:253]
	v_pk_add_f32 v[60:61], v[60:61], v[252:253]
	v_pk_add_f32 v[62:63], v[62:63], v[252:253]
	v_rcp_f32_e32 v56, v56
	v_rcp_f32_e32 v57, v57
	v_rcp_f32_e32 v58, v58
	v_rcp_f32_e32 v59, v59
	v_rcp_f32_e32 v60, v60
	v_rcp_f32_e32 v61, v61
	v_rcp_f32_e32 v62, v62
	v_rcp_f32_e32 v63, v63
	v_pk_mul_f32 v[56:57], v[52:53], v[56:57]
	v_pk_mul_f32 v[58:59], v[54:55], v[58:59]
	v_pk_mul_f32 v[60:61], v[48:49], v[60:61]
	v_pk_mul_f32 v[62:63], v[50:51], v[62:63]
	v_cvt_pk_bf16_f32 v56, v56, v57
	v_cvt_pk_bf16_f32 v57, v58, v59
	v_cvt_pk_bf16_f32 v58, v60, v61
	v_cvt_pk_bf16_f32 v59, v62, v63
	global_store_dwordx4 v174, v[56:59], s[60:61] offset:256
	s_add_u32 s60, s60, s64
	s_addc_u32 s61, s61, 0
	v_pk_mul_f32 v[48:49], v[44:45], v[44:45]
	v_pk_mul_f32 v[50:51], v[46:47], v[46:47]
	v_pk_mul_f32 v[52:53], v[40:41], v[40:41]
	v_pk_mul_f32 v[54:55], v[42:43], v[42:43]
	v_pk_fma_f32 v[48:49], v[48:49], s[98:99], v[250:251]
	v_pk_fma_f32 v[50:51], v[50:51], s[98:99], v[250:251]
	v_pk_fma_f32 v[52:53], v[52:53], s[98:99], v[250:251]
	v_pk_fma_f32 v[54:55], v[54:55], s[98:99], v[250:251]
	v_pk_mul_f32 v[48:49], v[44:45], v[48:49]
	v_pk_mul_f32 v[50:51], v[46:47], v[50:51]
	v_pk_mul_f32 v[52:53], v[40:41], v[52:53]
	v_pk_mul_f32 v[54:55], v[42:43], v[54:55]
	v_exp_f32_e32 v48, v48
	v_exp_f32_e32 v49, v49
	v_exp_f32_e32 v50, v50
	v_exp_f32_e32 v51, v51
	v_exp_f32_e32 v52, v52
	v_exp_f32_e32 v53, v53
	v_exp_f32_e32 v54, v54
	v_exp_f32_e32 v55, v55
	v_pk_add_f32 v[48:49], v[48:49], v[252:253]
	v_pk_add_f32 v[50:51], v[50:51], v[252:253]
	v_pk_add_f32 v[52:53], v[52:53], v[252:253]
	v_pk_add_f32 v[54:55], v[54:55], v[252:253]
	v_rcp_f32_e32 v48, v48
	v_rcp_f32_e32 v49, v49
	v_rcp_f32_e32 v50, v50
	v_rcp_f32_e32 v51, v51
	v_rcp_f32_e32 v52, v52
	v_rcp_f32_e32 v53, v53
	v_rcp_f32_e32 v54, v54
	v_rcp_f32_e32 v55, v55
	v_pk_mul_f32 v[48:49], v[44:45], v[48:49]
	v_pk_mul_f32 v[50:51], v[46:47], v[50:51]
	v_pk_mul_f32 v[52:53], v[40:41], v[52:53]
	v_pk_mul_f32 v[54:55], v[42:43], v[54:55]
	v_cvt_pk_bf16_f32 v48, v48, v49
	v_cvt_pk_bf16_f32 v49, v50, v51
	v_cvt_pk_bf16_f32 v50, v52, v53
	v_cvt_pk_bf16_f32 v51, v54, v55
	global_store_dwordx4 v174, v[48:51], s[60:61]
	v_pk_mul_f32 v[40:41], v[36:37], v[36:37]
	v_pk_mul_f32 v[42:43], v[38:39], v[38:39]
	v_pk_mul_f32 v[44:45], v[32:33], v[32:33]
	v_pk_mul_f32 v[46:47], v[34:35], v[34:35]
	v_pk_fma_f32 v[40:41], v[40:41], s[98:99], v[250:251]
	v_pk_fma_f32 v[42:43], v[42:43], s[98:99], v[250:251]
	v_pk_fma_f32 v[44:45], v[44:45], s[98:99], v[250:251]
	v_pk_fma_f32 v[46:47], v[46:47], s[98:99], v[250:251]
	v_pk_mul_f32 v[40:41], v[36:37], v[40:41]
	v_pk_mul_f32 v[42:43], v[38:39], v[42:43]
	v_pk_mul_f32 v[44:45], v[32:33], v[44:45]
	v_pk_mul_f32 v[46:47], v[34:35], v[46:47]
	v_exp_f32_e32 v40, v40
	v_exp_f32_e32 v41, v41
	v_exp_f32_e32 v42, v42
	v_exp_f32_e32 v43, v43
	v_exp_f32_e32 v44, v44
	v_exp_f32_e32 v45, v45
	v_exp_f32_e32 v46, v46
	v_exp_f32_e32 v47, v47
	v_pk_add_f32 v[40:41], v[40:41], v[252:253]
	v_pk_add_f32 v[42:43], v[42:43], v[252:253]
	v_pk_add_f32 v[44:45], v[44:45], v[252:253]
	v_pk_add_f32 v[46:47], v[46:47], v[252:253]
	v_rcp_f32_e32 v40, v40
	v_rcp_f32_e32 v41, v41
	v_rcp_f32_e32 v42, v42
	v_rcp_f32_e32 v43, v43
	v_rcp_f32_e32 v44, v44
	v_rcp_f32_e32 v45, v45
	v_rcp_f32_e32 v46, v46
	v_rcp_f32_e32 v47, v47
	v_pk_mul_f32 v[40:41], v[36:37], v[40:41]
	v_pk_mul_f32 v[42:43], v[38:39], v[42:43]
	v_pk_mul_f32 v[44:45], v[32:33], v[44:45]
	v_pk_mul_f32 v[46:47], v[34:35], v[46:47]
	v_cvt_pk_bf16_f32 v40, v40, v41
	v_cvt_pk_bf16_f32 v41, v42, v43
	v_cvt_pk_bf16_f32 v42, v44, v45
	v_cvt_pk_bf16_f32 v43, v46, v47
	global_store_dwordx4 v174, v[40:43], s[60:61] offset:256
	s_add_u32 s60, s60, s64
	s_addc_u32 s61, s61, 0
	v_pk_mul_f32 v[32:33], v[28:29], v[28:29]
	v_pk_mul_f32 v[34:35], v[30:31], v[30:31]
	v_pk_mul_f32 v[36:37], v[24:25], v[24:25]
	v_pk_mul_f32 v[38:39], v[26:27], v[26:27]
	v_pk_fma_f32 v[32:33], v[32:33], s[98:99], v[250:251]
	v_pk_fma_f32 v[34:35], v[34:35], s[98:99], v[250:251]
	v_pk_fma_f32 v[36:37], v[36:37], s[98:99], v[250:251]
	v_pk_fma_f32 v[38:39], v[38:39], s[98:99], v[250:251]
	v_pk_mul_f32 v[32:33], v[28:29], v[32:33]
	v_pk_mul_f32 v[34:35], v[30:31], v[34:35]
	v_pk_mul_f32 v[36:37], v[24:25], v[36:37]
	v_pk_mul_f32 v[38:39], v[26:27], v[38:39]
	v_exp_f32_e32 v32, v32
	v_exp_f32_e32 v33, v33
	v_exp_f32_e32 v34, v34
	v_exp_f32_e32 v35, v35
	v_exp_f32_e32 v36, v36
	v_exp_f32_e32 v37, v37
	v_exp_f32_e32 v38, v38
	v_exp_f32_e32 v39, v39
	v_pk_add_f32 v[32:33], v[32:33], v[252:253]
	v_pk_add_f32 v[34:35], v[34:35], v[252:253]
	v_pk_add_f32 v[36:37], v[36:37], v[252:253]
	v_pk_add_f32 v[38:39], v[38:39], v[252:253]
	v_rcp_f32_e32 v32, v32
	v_rcp_f32_e32 v33, v33
	v_rcp_f32_e32 v34, v34
	v_rcp_f32_e32 v35, v35
	v_rcp_f32_e32 v36, v36
	v_rcp_f32_e32 v37, v37
	v_rcp_f32_e32 v38, v38
	v_rcp_f32_e32 v39, v39
	v_pk_mul_f32 v[32:33], v[28:29], v[32:33]
	v_pk_mul_f32 v[34:35], v[30:31], v[34:35]
	v_pk_mul_f32 v[36:37], v[24:25], v[36:37]
	v_pk_mul_f32 v[38:39], v[26:27], v[38:39]
	v_cvt_pk_bf16_f32 v32, v32, v33
	v_cvt_pk_bf16_f32 v33, v34, v35
	v_cvt_pk_bf16_f32 v34, v36, v37
	v_cvt_pk_bf16_f32 v35, v38, v39
	global_store_dwordx4 v174, v[32:35], s[60:61]
	v_pk_mul_f32 v[24:25], v[20:21], v[20:21]
	v_pk_mul_f32 v[26:27], v[22:23], v[22:23]
	v_pk_mul_f32 v[28:29], v[16:17], v[16:17]
	v_pk_mul_f32 v[30:31], v[18:19], v[18:19]
	v_pk_fma_f32 v[24:25], v[24:25], s[98:99], v[250:251]
	v_pk_fma_f32 v[26:27], v[26:27], s[98:99], v[250:251]
	v_pk_fma_f32 v[28:29], v[28:29], s[98:99], v[250:251]
	v_pk_fma_f32 v[30:31], v[30:31], s[98:99], v[250:251]
	v_pk_mul_f32 v[24:25], v[20:21], v[24:25]
	v_pk_mul_f32 v[26:27], v[22:23], v[26:27]
	v_pk_mul_f32 v[28:29], v[16:17], v[28:29]
	v_pk_mul_f32 v[30:31], v[18:19], v[30:31]
	v_exp_f32_e32 v24, v24
	v_exp_f32_e32 v25, v25
	v_exp_f32_e32 v26, v26
	v_exp_f32_e32 v27, v27
	v_exp_f32_e32 v28, v28
	v_exp_f32_e32 v29, v29
	v_exp_f32_e32 v30, v30
	v_exp_f32_e32 v31, v31
	v_pk_add_f32 v[24:25], v[24:25], v[252:253]
	v_pk_add_f32 v[26:27], v[26:27], v[252:253]
	v_pk_add_f32 v[28:29], v[28:29], v[252:253]
	v_pk_add_f32 v[30:31], v[30:31], v[252:253]
	v_rcp_f32_e32 v24, v24
	v_rcp_f32_e32 v25, v25
	v_rcp_f32_e32 v26, v26
	v_rcp_f32_e32 v27, v27
	v_rcp_f32_e32 v28, v28
	v_rcp_f32_e32 v29, v29
	v_rcp_f32_e32 v30, v30
	v_rcp_f32_e32 v31, v31
	v_pk_mul_f32 v[24:25], v[20:21], v[24:25]
	v_pk_mul_f32 v[26:27], v[22:23], v[26:27]
	v_pk_mul_f32 v[28:29], v[16:17], v[28:29]
	v_pk_mul_f32 v[30:31], v[18:19], v[30:31]
	v_cvt_pk_bf16_f32 v24, v24, v25
	v_cvt_pk_bf16_f32 v25, v26, v27
	v_cvt_pk_bf16_f32 v26, v28, v29
	v_cvt_pk_bf16_f32 v27, v30, v31
	global_store_dwordx4 v174, v[24:27], s[60:61] offset:256
	s_add_u32 s60, s60, s64
	s_addc_u32 s61, s61, 0
	v_pk_mul_f32 v[16:17], v[12:13], v[12:13]
	v_pk_mul_f32 v[18:19], v[14:15], v[14:15]
	v_pk_mul_f32 v[20:21], v[8:9], v[8:9]
	v_pk_mul_f32 v[22:23], v[10:11], v[10:11]
	v_pk_fma_f32 v[16:17], v[16:17], s[98:99], v[250:251]
	v_pk_fma_f32 v[18:19], v[18:19], s[98:99], v[250:251]
	v_pk_fma_f32 v[20:21], v[20:21], s[98:99], v[250:251]
	v_pk_fma_f32 v[22:23], v[22:23], s[98:99], v[250:251]
	v_pk_mul_f32 v[16:17], v[12:13], v[16:17]
	v_pk_mul_f32 v[18:19], v[14:15], v[18:19]
	v_pk_mul_f32 v[20:21], v[8:9], v[20:21]
	v_pk_mul_f32 v[22:23], v[10:11], v[22:23]
	v_exp_f32_e32 v16, v16
	v_exp_f32_e32 v17, v17
	v_exp_f32_e32 v18, v18
	v_exp_f32_e32 v19, v19
	v_exp_f32_e32 v20, v20
	v_exp_f32_e32 v21, v21
	v_exp_f32_e32 v22, v22
	v_exp_f32_e32 v23, v23
	v_pk_add_f32 v[16:17], v[16:17], v[252:253]
	v_pk_add_f32 v[18:19], v[18:19], v[252:253]
	v_pk_add_f32 v[20:21], v[20:21], v[252:253]
	v_pk_add_f32 v[22:23], v[22:23], v[252:253]
	v_rcp_f32_e32 v16, v16
	v_rcp_f32_e32 v17, v17
	v_rcp_f32_e32 v18, v18
	v_rcp_f32_e32 v19, v19
	v_rcp_f32_e32 v20, v20
	v_rcp_f32_e32 v21, v21
	v_rcp_f32_e32 v22, v22
	v_rcp_f32_e32 v23, v23
	v_pk_mul_f32 v[16:17], v[12:13], v[16:17]
	v_pk_mul_f32 v[18:19], v[14:15], v[18:19]
	v_pk_mul_f32 v[20:21], v[8:9], v[20:21]
	v_pk_mul_f32 v[22:23], v[10:11], v[22:23]
	v_cvt_pk_bf16_f32 v16, v16, v17
	v_cvt_pk_bf16_f32 v17, v18, v19
	v_cvt_pk_bf16_f32 v18, v20, v21
	v_cvt_pk_bf16_f32 v19, v22, v23
	global_store_dwordx4 v174, v[16:19], s[60:61]
	v_pk_mul_f32 v[8:9], v[4:5], v[4:5]
	v_pk_mul_f32 v[10:11], v[6:7], v[6:7]
	v_pk_mul_f32 v[12:13], v[0:1], v[0:1]
	v_pk_mul_f32 v[14:15], v[2:3], v[2:3]
	v_pk_fma_f32 v[8:9], v[8:9], s[98:99], v[250:251]
	v_pk_fma_f32 v[10:11], v[10:11], s[98:99], v[250:251]
	v_pk_fma_f32 v[12:13], v[12:13], s[98:99], v[250:251]
	v_pk_fma_f32 v[14:15], v[14:15], s[98:99], v[250:251]
	v_pk_mul_f32 v[8:9], v[4:5], v[8:9]
	v_pk_mul_f32 v[10:11], v[6:7], v[10:11]
	v_pk_mul_f32 v[12:13], v[0:1], v[12:13]
	v_pk_mul_f32 v[14:15], v[2:3], v[14:15]
	v_exp_f32_e32 v8, v8
	v_exp_f32_e32 v9, v9
	v_exp_f32_e32 v10, v10
	v_exp_f32_e32 v11, v11
	v_exp_f32_e32 v12, v12
	v_exp_f32_e32 v13, v13
	v_exp_f32_e32 v14, v14
	v_exp_f32_e32 v15, v15
	v_pk_add_f32 v[8:9], v[8:9], v[252:253]
	v_pk_add_f32 v[10:11], v[10:11], v[252:253]
	v_pk_add_f32 v[12:13], v[12:13], v[252:253]
	v_pk_add_f32 v[14:15], v[14:15], v[252:253]
	v_rcp_f32_e32 v8, v8
	v_rcp_f32_e32 v9, v9
	v_rcp_f32_e32 v10, v10
	v_rcp_f32_e32 v11, v11
	v_rcp_f32_e32 v12, v12
	v_rcp_f32_e32 v13, v13
	v_rcp_f32_e32 v14, v14
	v_rcp_f32_e32 v15, v15
	v_pk_mul_f32 v[8:9], v[4:5], v[8:9]
	v_pk_mul_f32 v[10:11], v[6:7], v[10:11]
	v_pk_mul_f32 v[12:13], v[0:1], v[12:13]
	v_pk_mul_f32 v[14:15], v[2:3], v[14:15]
	v_cvt_pk_bf16_f32 v8, v8, v9
	v_cvt_pk_bf16_f32 v9, v10, v11
	v_cvt_pk_bf16_f32 v10, v12, v13
	v_cvt_pk_bf16_f32 v11, v14, v15
	global_store_dwordx4 v174, v[8:11], s[60:61] offset:256
	s_branch .Lwin_done
.Lwin_act2:
	v_pk_mul_f32 v[128:129], v[124:125], s[100:101]
	v_pk_mul_f32 v[130:131], v[126:127], s[100:101]
	v_pk_mul_f32 v[132:133], v[120:121], s[100:101]
	v_pk_mul_f32 v[134:135], v[122:123], s[100:101]
	v_exp_f32_e32 v128, v128
	v_exp_f32_e32 v129, v129
	v_exp_f32_e32 v130, v130
	v_exp_f32_e32 v131, v131
	v_exp_f32_e32 v132, v132
	v_exp_f32_e32 v133, v133
	v_exp_f32_e32 v134, v134
	v_exp_f32_e32 v135, v135
	v_pk_add_f32 v[128:129], v[128:129], v[252:253]
	v_pk_add_f32 v[130:131], v[130:131], v[252:253]
	v_pk_add_f32 v[132:133], v[132:133], v[252:253]
	v_pk_add_f32 v[134:135], v[134:135], v[252:253]
	v_rcp_f32_e32 v128, v128
	v_rcp_f32_e32 v129, v129
	v_rcp_f32_e32 v130, v130
	v_rcp_f32_e32 v131, v131
	v_rcp_f32_e32 v132, v132
	v_rcp_f32_e32 v133, v133
	v_rcp_f32_e32 v134, v134
	v_rcp_f32_e32 v135, v135
	s_nop 0
	v_cvt_pk_bf16_f32 v128, v128, v129
	v_cvt_pk_bf16_f32 v129, v130, v131
	v_cvt_pk_bf16_f32 v130, v132, v133
	v_cvt_pk_bf16_f32 v131, v134, v135
	global_store_dwordx4 v174, v[128:131], s[60:61]
	v_pk_mul_f32 v[120:121], v[116:117], s[100:101]
	v_pk_mul_f32 v[122:123], v[118:119], s[100:101]
	v_pk_mul_f32 v[124:125], v[112:113], s[100:101]
	v_pk_mul_f32 v[126:127], v[114:115], s[100:101]
	v_exp_f32_e32 v120, v120
	v_exp_f32_e32 v121, v121
	v_exp_f32_e32 v122, v122
	v_exp_f32_e32 v123, v123
	v_exp_f32_e32 v124, v124
	v_exp_f32_e32 v125, v125
	v_exp_f32_e32 v126, v126
	v_exp_f32_e32 v127, v127
	v_pk_add_f32 v[120:121], v[120:121], v[252:253]
	v_pk_add_f32 v[122:123], v[122:123], v[252:253]
	v_pk_add_f32 v[124:125], v[124:125], v[252:253]
	v_pk_add_f32 v[126:127], v[126:127], v[252:253]
	v_rcp_f32_e32 v120, v120
	v_rcp_f32_e32 v121, v121
	v_rcp_f32_e32 v122, v122
	v_rcp_f32_e32 v123, v123
	v_rcp_f32_e32 v124, v124
	v_rcp_f32_e32 v125, v125
	v_rcp_f32_e32 v126, v126
	v_rcp_f32_e32 v127, v127
	s_nop 0
	v_cvt_pk_bf16_f32 v120, v120, v121
	v_cvt_pk_bf16_f32 v121, v122, v123
	v_cvt_pk_bf16_f32 v122, v124, v125
	v_cvt_pk_bf16_f32 v123, v126, v127
	global_store_dwordx4 v174, v[120:123], s[60:61] offset:256
	s_add_u32 s60, s60, s64
	s_addc_u32 s61, s61, 0
	v_pk_mul_f32 v[112:113], v[108:109], s[100:101]
	v_pk_mul_f32 v[114:115], v[110:111], s[100:101]
	v_pk_mul_f32 v[116:117], v[104:105], s[100:101]
	v_pk_mul_f32 v[118:119], v[106:107], s[100:101]
	v_exp_f32_e32 v112, v112
	v_exp_f32_e32 v113, v113
	v_exp_f32_e32 v114, v114
	v_exp_f32_e32 v115, v115
	v_exp_f32_e32 v116, v116
	v_exp_f32_e32 v117, v117
	v_exp_f32_e32 v118, v118
	v_exp_f32_e32 v119, v119
	v_pk_add_f32 v[112:113], v[112:113], v[252:253]
	v_pk_add_f32 v[114:115], v[114:115], v[252:253]
	v_pk_add_f32 v[116:117], v[116:117], v[252:253]
	v_pk_add_f32 v[118:119], v[118:119], v[252:253]
	v_rcp_f32_e32 v112, v112
	v_rcp_f32_e32 v113, v113
	v_rcp_f32_e32 v114, v114
	v_rcp_f32_e32 v115, v115
	v_rcp_f32_e32 v116, v116
	v_rcp_f32_e32 v117, v117
	v_rcp_f32_e32 v118, v118
	v_rcp_f32_e32 v119, v119
	s_nop 0
	v_cvt_pk_bf16_f32 v112, v112, v113
	v_cvt_pk_bf16_f32 v113, v114, v115
	v_cvt_pk_bf16_f32 v114, v116, v117
	v_cvt_pk_bf16_f32 v115, v118, v119
	global_store_dwordx4 v174, v[112:115], s[60:61]
	v_pk_mul_f32 v[104:105], v[100:101], s[100:101]
	v_pk_mul_f32 v[106:107], v[102:103], s[100:101]
	v_pk_mul_f32 v[108:109], v[96:97], s[100:101]
	v_pk_mul_f32 v[110:111], v[98:99], s[100:101]
	v_exp_f32_e32 v104, v104
	v_exp_f32_e32 v105, v105
	v_exp_f32_e32 v106, v106
	v_exp_f32_e32 v107, v107
	v_exp_f32_e32 v108, v108
	v_exp_f32_e32 v109, v109
	v_exp_f32_e32 v110, v110
	v_exp_f32_e32 v111, v111
	v_pk_add_f32 v[104:105], v[104:105], v[252:253]
	v_pk_add_f32 v[106:107], v[106:107], v[252:253]
	v_pk_add_f32 v[108:109], v[108:109], v[252:253]
	v_pk_add_f32 v[110:111], v[110:111], v[252:253]
	v_rcp_f32_e32 v104, v104
	v_rcp_f32_e32 v105, v105
	v_rcp_f32_e32 v106, v106
	v_rcp_f32_e32 v107, v107
	v_rcp_f32_e32 v108, v108
	v_rcp_f32_e32 v109, v109
	v_rcp_f32_e32 v110, v110
	v_rcp_f32_e32 v111, v111
	s_nop 0
	v_cvt_pk_bf16_f32 v104, v104, v105
	v_cvt_pk_bf16_f32 v105, v106, v107
	v_cvt_pk_bf16_f32 v106, v108, v109
	v_cvt_pk_bf16_f32 v107, v110, v111
	global_store_dwordx4 v174, v[104:107], s[60:61] offset:256
	s_add_u32 s60, s60, s64
	s_addc_u32 s61, s61, 0
	v_pk_mul_f32 v[96:97], v[92:93], s[100:101]
	v_pk_mul_f32 v[98:99], v[94:95], s[100:101]
	v_pk_mul_f32 v[100:101], v[88:89], s[100:101]
	v_pk_mul_f32 v[102:103], v[90:91], s[100:101]
	v_exp_f32_e32 v96, v96
	v_exp_f32_e32 v97, v97
	v_exp_f32_e32 v98, v98
	v_exp_f32_e32 v99, v99
	v_exp_f32_e32 v100, v100
	v_exp_f32_e32 v101, v101
	v_exp_f32_e32 v102, v102
	v_exp_f32_e32 v103, v103
	v_pk_add_f32 v[96:97], v[96:97], v[252:253]
	v_pk_add_f32 v[98:99], v[98:99], v[252:253]
	v_pk_add_f32 v[100:101], v[100:101], v[252:253]
	v_pk_add_f32 v[102:103], v[102:103], v[252:253]
	v_rcp_f32_e32 v96, v96
	v_rcp_f32_e32 v97, v97
	v_rcp_f32_e32 v98, v98
	v_rcp_f32_e32 v99, v99
	v_rcp_f32_e32 v100, v100
	v_rcp_f32_e32 v101, v101
	v_rcp_f32_e32 v102, v102
	v_rcp_f32_e32 v103, v103
	s_nop 0
	v_cvt_pk_bf16_f32 v96, v96, v97
	v_cvt_pk_bf16_f32 v97, v98, v99
	v_cvt_pk_bf16_f32 v98, v100, v101
	v_cvt_pk_bf16_f32 v99, v102, v103
	global_store_dwordx4 v174, v[96:99], s[60:61]
	v_pk_mul_f32 v[88:89], v[84:85], s[100:101]
	v_pk_mul_f32 v[90:91], v[86:87], s[100:101]
	v_pk_mul_f32 v[92:93], v[80:81], s[100:101]
	v_pk_mul_f32 v[94:95], v[82:83], s[100:101]
	v_exp_f32_e32 v88, v88
	v_exp_f32_e32 v89, v89
	v_exp_f32_e32 v90, v90
	v_exp_f32_e32 v91, v91
	v_exp_f32_e32 v92, v92
	v_exp_f32_e32 v93, v93
	v_exp_f32_e32 v94, v94
	v_exp_f32_e32 v95, v95
	v_pk_add_f32 v[88:89], v[88:89], v[252:253]
	v_pk_add_f32 v[90:91], v[90:91], v[252:253]
	v_pk_add_f32 v[92:93], v[92:93], v[252:253]
	v_pk_add_f32 v[94:95], v[94:95], v[252:253]
	v_rcp_f32_e32 v88, v88
	v_rcp_f32_e32 v89, v89
	v_rcp_f32_e32 v90, v90
	v_rcp_f32_e32 v91, v91
	v_rcp_f32_e32 v92, v92
	v_rcp_f32_e32 v93, v93
	v_rcp_f32_e32 v94, v94
	v_rcp_f32_e32 v95, v95
	s_nop 0
	v_cvt_pk_bf16_f32 v88, v88, v89
	v_cvt_pk_bf16_f32 v89, v90, v91
	v_cvt_pk_bf16_f32 v90, v92, v93
	v_cvt_pk_bf16_f32 v91, v94, v95
	global_store_dwordx4 v174, v[88:91], s[60:61] offset:256
	s_add_u32 s60, s60, s64
	s_addc_u32 s61, s61, 0
	v_pk_mul_f32 v[80:81], v[76:77], s[100:101]
	v_pk_mul_f32 v[82:83], v[78:79], s[100:101]
	v_pk_mul_f32 v[84:85], v[72:73], s[100:101]
	v_pk_mul_f32 v[86:87], v[74:75], s[100:101]
	v_exp_f32_e32 v80, v80
	v_exp_f32_e32 v81, v81
	v_exp_f32_e32 v82, v82
	v_exp_f32_e32 v83, v83
	v_exp_f32_e32 v84, v84
	v_exp_f32_e32 v85, v85
	v_exp_f32_e32 v86, v86
	v_exp_f32_e32 v87, v87
	v_pk_add_f32 v[80:81], v[80:81], v[252:253]
	v_pk_add_f32 v[82:83], v[82:83], v[252:253]
	v_pk_add_f32 v[84:85], v[84:85], v[252:253]
	v_pk_add_f32 v[86:87], v[86:87], v[252:253]
	v_rcp_f32_e32 v80, v80
	v_rcp_f32_e32 v81, v81
	v_rcp_f32_e32 v82, v82
	v_rcp_f32_e32 v83, v83
	v_rcp_f32_e32 v84, v84
	v_rcp_f32_e32 v85, v85
	v_rcp_f32_e32 v86, v86
	v_rcp_f32_e32 v87, v87
	s_nop 0
	v_cvt_pk_bf16_f32 v80, v80, v81
	v_cvt_pk_bf16_f32 v81, v82, v83
	v_cvt_pk_bf16_f32 v82, v84, v85
	v_cvt_pk_bf16_f32 v83, v86, v87
	global_store_dwordx4 v174, v[80:83], s[60:61]
	v_pk_mul_f32 v[72:73], v[68:69], s[100:101]
	v_pk_mul_f32 v[74:75], v[70:71], s[100:101]
	v_pk_mul_f32 v[76:77], v[64:65], s[100:101]
	v_pk_mul_f32 v[78:79], v[66:67], s[100:101]
	v_exp_f32_e32 v72, v72
	v_exp_f32_e32 v73, v73
	v_exp_f32_e32 v74, v74
	v_exp_f32_e32 v75, v75
	v_exp_f32_e32 v76, v76
	v_exp_f32_e32 v77, v77
	v_exp_f32_e32 v78, v78
	v_exp_f32_e32 v79, v79
	v_pk_add_f32 v[72:73], v[72:73], v[252:253]
	v_pk_add_f32 v[74:75], v[74:75], v[252:253]
	v_pk_add_f32 v[76:77], v[76:77], v[252:253]
	v_pk_add_f32 v[78:79], v[78:79], v[252:253]
	v_rcp_f32_e32 v72, v72
	v_rcp_f32_e32 v73, v73
	v_rcp_f32_e32 v74, v74
	v_rcp_f32_e32 v75, v75
	v_rcp_f32_e32 v76, v76
	v_rcp_f32_e32 v77, v77
	v_rcp_f32_e32 v78, v78
	v_rcp_f32_e32 v79, v79
	s_nop 0
	v_cvt_pk_bf16_f32 v72, v72, v73
	v_cvt_pk_bf16_f32 v73, v74, v75
	v_cvt_pk_bf16_f32 v74, v76, v77
	v_cvt_pk_bf16_f32 v75, v78, v79
	global_store_dwordx4 v174, v[72:75], s[60:61] offset:256
	s_add_u32 s60, s60, s64
	s_addc_u32 s61, s61, 0
	s_add_u32 s60, s60, s65
	s_addc_u32 s61, s61, 0
	v_pk_mul_f32 v[64:65], v[60:61], s[100:101]
	v_pk_mul_f32 v[66:67], v[62:63], s[100:101]
	v_pk_mul_f32 v[68:69], v[56:57], s[100:101]
	v_pk_mul_f32 v[70:71], v[58:59], s[100:101]
	v_exp_f32_e32 v64, v64
	v_exp_f32_e32 v65, v65
	v_exp_f32_e32 v66, v66
	v_exp_f32_e32 v67, v67
	v_exp_f32_e32 v68, v68
	v_exp_f32_e32 v69, v69
	v_exp_f32_e32 v70, v70
	v_exp_f32_e32 v71, v71
	v_pk_add_f32 v[64:65], v[64:65], v[252:253]
	v_pk_add_f32 v[66:67], v[66:67], v[252:253]
	v_pk_add_f32 v[68:69], v[68:69], v[252:253]
	v_pk_add_f32 v[70:71], v[70:71], v[252:253]
	v_rcp_f32_e32 v64, v64
	v_rcp_f32_e32 v65, v65
	v_rcp_f32_e32 v66, v66
	v_rcp_f32_e32 v67, v67
	v_rcp_f32_e32 v68, v68
	v_rcp_f32_e32 v69, v69
	v_rcp_f32_e32 v70, v70
	v_rcp_f32_e32 v71, v71
	s_nop 0
	v_cvt_pk_bf16_f32 v64, v64, v65
	v_cvt_pk_bf16_f32 v65, v66, v67
	v_cvt_pk_bf16_f32 v66, v68, v69
	v_cvt_pk_bf16_f32 v67, v70, v71
	global_store_dwordx4 v174, v[64:67], s[60:61]
	v_pk_mul_f32 v[56:57], v[52:53], s[100:101]
	v_pk_mul_f32 v[58:59], v[54:55], s[100:101]
	v_pk_mul_f32 v[60:61], v[48:49], s[100:101]
	v_pk_mul_f32 v[62:63], v[50:51], s[100:101]
	v_exp_f32_e32 v56, v56
	v_exp_f32_e32 v57, v57
	v_exp_f32_e32 v58, v58
	v_exp_f32_e32 v59, v59
	v_exp_f32_e32 v60, v60
	v_exp_f32_e32 v61, v61
	v_exp_f32_e32 v62, v62
	v_exp_f32_e32 v63, v63
	v_pk_add_f32 v[56:57], v[56:57], v[252:253]
	v_pk_add_f32 v[58:59], v[58:59], v[252:253]
	v_pk_add_f32 v[60:61], v[60:61], v[252:253]
	v_pk_add_f32 v[62:63], v[62:63], v[252:253]
	v_rcp_f32_e32 v56, v56
	v_rcp_f32_e32 v57, v57
	v_rcp_f32_e32 v58, v58
	v_rcp_f32_e32 v59, v59
	v_rcp_f32_e32 v60, v60
	v_rcp_f32_e32 v61, v61
	v_rcp_f32_e32 v62, v62
	v_rcp_f32_e32 v63, v63
	s_nop 0
	v_cvt_pk_bf16_f32 v56, v56, v57
	v_cvt_pk_bf16_f32 v57, v58, v59
	v_cvt_pk_bf16_f32 v58, v60, v61
	v_cvt_pk_bf16_f32 v59, v62, v63
	global_store_dwordx4 v174, v[56:59], s[60:61] offset:256
	s_add_u32 s60, s60, s64
	s_addc_u32 s61, s61, 0
	v_pk_mul_f32 v[48:49], v[44:45], s[100:101]
	v_pk_mul_f32 v[50:51], v[46:47], s[100:101]
	v_pk_mul_f32 v[52:53], v[40:41], s[100:101]
	v_pk_mul_f32 v[54:55], v[42:43], s[100:101]
	v_exp_f32_e32 v48, v48
	v_exp_f32_e32 v49, v49
	v_exp_f32_e32 v50, v50
	v_exp_f32_e32 v51, v51
	v_exp_f32_e32 v52, v52
	v_exp_f32_e32 v53, v53
	v_exp_f32_e32 v54, v54
	v_exp_f32_e32 v55, v55
	v_pk_add_f32 v[48:49], v[48:49], v[252:253]
	v_pk_add_f32 v[50:51], v[50:51], v[252:253]
	v_pk_add_f32 v[52:53], v[52:53], v[252:253]
	v_pk_add_f32 v[54:55], v[54:55], v[252:253]
	v_rcp_f32_e32 v48, v48
	v_rcp_f32_e32 v49, v49
	v_rcp_f32_e32 v50, v50
	v_rcp_f32_e32 v51, v51
	v_rcp_f32_e32 v52, v52
	v_rcp_f32_e32 v53, v53
	v_rcp_f32_e32 v54, v54
	v_rcp_f32_e32 v55, v55
	s_nop 0
	v_cvt_pk_bf16_f32 v48, v48, v49
	v_cvt_pk_bf16_f32 v49, v50, v51
	v_cvt_pk_bf16_f32 v50, v52, v53
	v_cvt_pk_bf16_f32 v51, v54, v55
	global_store_dwordx4 v174, v[48:51], s[60:61]
	v_pk_mul_f32 v[40:41], v[36:37], s[100:101]
	v_pk_mul_f32 v[42:43], v[38:39], s[100:101]
	v_pk_mul_f32 v[44:45], v[32:33], s[100:101]
	v_pk_mul_f32 v[46:47], v[34:35], s[100:101]
	v_exp_f32_e32 v40, v40
	v_exp_f32_e32 v41, v41
	v_exp_f32_e32 v42, v42
	v_exp_f32_e32 v43, v43
	v_exp_f32_e32 v44, v44
	v_exp_f32_e32 v45, v45
	v_exp_f32_e32 v46, v46
	v_exp_f32_e32 v47, v47
	v_pk_add_f32 v[40:41], v[40:41], v[252:253]
	v_pk_add_f32 v[42:43], v[42:43], v[252:253]
	v_pk_add_f32 v[44:45], v[44:45], v[252:253]
	v_pk_add_f32 v[46:47], v[46:47], v[252:253]
	v_rcp_f32_e32 v40, v40
	v_rcp_f32_e32 v41, v41
	v_rcp_f32_e32 v42, v42
	v_rcp_f32_e32 v43, v43
	v_rcp_f32_e32 v44, v44
	v_rcp_f32_e32 v45, v45
	v_rcp_f32_e32 v46, v46
	v_rcp_f32_e32 v47, v47
	s_nop 0
	v_cvt_pk_bf16_f32 v40, v40, v41
	v_cvt_pk_bf16_f32 v41, v42, v43
	v_cvt_pk_bf16_f32 v42, v44, v45
	v_cvt_pk_bf16_f32 v43, v46, v47
	global_store_dwordx4 v174, v[40:43], s[60:61] offset:256
	s_add_u32 s60, s60, s64
	s_addc_u32 s61, s61, 0
	v_pk_mul_f32 v[32:33], v[28:29], s[100:101]
	v_pk_mul_f32 v[34:35], v[30:31], s[100:101]
	v_pk_mul_f32 v[36:37], v[24:25], s[100:101]
	v_pk_mul_f32 v[38:39], v[26:27], s[100:101]
	v_exp_f32_e32 v32, v32
	v_exp_f32_e32 v33, v33
	v_exp_f32_e32 v34, v34
	v_exp_f32_e32 v35, v35
	v_exp_f32_e32 v36, v36
	v_exp_f32_e32 v37, v37
	v_exp_f32_e32 v38, v38
	v_exp_f32_e32 v39, v39
	v_pk_add_f32 v[32:33], v[32:33], v[252:253]
	v_pk_add_f32 v[34:35], v[34:35], v[252:253]
	v_pk_add_f32 v[36:37], v[36:37], v[252:253]
	v_pk_add_f32 v[38:39], v[38:39], v[252:253]
	v_rcp_f32_e32 v32, v32
	v_rcp_f32_e32 v33, v33
	v_rcp_f32_e32 v34, v34
	v_rcp_f32_e32 v35, v35
	v_rcp_f32_e32 v36, v36
	v_rcp_f32_e32 v37, v37
	v_rcp_f32_e32 v38, v38
	v_rcp_f32_e32 v39, v39
	s_nop 0
	v_cvt_pk_bf16_f32 v32, v32, v33
	v_cvt_pk_bf16_f32 v33, v34, v35
	v_cvt_pk_bf16_f32 v34, v36, v37
	v_cvt_pk_bf16_f32 v35, v38, v39
	global_store_dwordx4 v174, v[32:35], s[60:61]
	v_pk_mul_f32 v[24:25], v[20:21], s[100:101]
	v_pk_mul_f32 v[26:27], v[22:23], s[100:101]
	v_pk_mul_f32 v[28:29], v[16:17], s[100:101]
	v_pk_mul_f32 v[30:31], v[18:19], s[100:101]
	v_exp_f32_e32 v24, v24
	v_exp_f32_e32 v25, v25
	v_exp_f32_e32 v26, v26
	v_exp_f32_e32 v27, v27
	v_exp_f32_e32 v28, v28
	v_exp_f32_e32 v29, v29
	v_exp_f32_e32 v30, v30
	v_exp_f32_e32 v31, v31
	v_pk_add_f32 v[24:25], v[24:25], v[252:253]
	v_pk_add_f32 v[26:27], v[26:27], v[252:253]
	v_pk_add_f32 v[28:29], v[28:29], v[252:253]
	v_pk_add_f32 v[30:31], v[30:31], v[252:253]
	v_rcp_f32_e32 v24, v24
	v_rcp_f32_e32 v25, v25
	v_rcp_f32_e32 v26, v26
	v_rcp_f32_e32 v27, v27
	v_rcp_f32_e32 v28, v28
	v_rcp_f32_e32 v29, v29
	v_rcp_f32_e32 v30, v30
	v_rcp_f32_e32 v31, v31
	s_nop 0
	v_cvt_pk_bf16_f32 v24, v24, v25
	v_cvt_pk_bf16_f32 v25, v26, v27
	v_cvt_pk_bf16_f32 v26, v28, v29
	v_cvt_pk_bf16_f32 v27, v30, v31
	global_store_dwordx4 v174, v[24:27], s[60:61] offset:256
	s_add_u32 s60, s60, s64
	s_addc_u32 s61, s61, 0
	v_pk_mul_f32 v[16:17], v[12:13], s[100:101]
	v_pk_mul_f32 v[18:19], v[14:15], s[100:101]
	v_pk_mul_f32 v[20:21], v[8:9], s[100:101]
	v_pk_mul_f32 v[22:23], v[10:11], s[100:101]
	v_exp_f32_e32 v16, v16
	v_exp_f32_e32 v17, v17
	v_exp_f32_e32 v18, v18
	v_exp_f32_e32 v19, v19
	v_exp_f32_e32 v20, v20
	v_exp_f32_e32 v21, v21
	v_exp_f32_e32 v22, v22
	v_exp_f32_e32 v23, v23
	v_pk_add_f32 v[16:17], v[16:17], v[252:253]
	v_pk_add_f32 v[18:19], v[18:19], v[252:253]
	v_pk_add_f32 v[20:21], v[20:21], v[252:253]
	v_pk_add_f32 v[22:23], v[22:23], v[252:253]
	v_rcp_f32_e32 v16, v16
	v_rcp_f32_e32 v17, v17
	v_rcp_f32_e32 v18, v18
	v_rcp_f32_e32 v19, v19
	v_rcp_f32_e32 v20, v20
	v_rcp_f32_e32 v21, v21
	v_rcp_f32_e32 v22, v22
	v_rcp_f32_e32 v23, v23
	s_nop 0
	v_cvt_pk_bf16_f32 v16, v16, v17
	v_cvt_pk_bf16_f32 v17, v18, v19
	v_cvt_pk_bf16_f32 v18, v20, v21
	v_cvt_pk_bf16_f32 v19, v22, v23
	global_store_dwordx4 v174, v[16:19], s[60:61]
	v_pk_mul_f32 v[8:9], v[4:5], s[100:101]
	v_pk_mul_f32 v[10:11], v[6:7], s[100:101]
	v_pk_mul_f32 v[12:13], v[0:1], s[100:101]
	v_pk_mul_f32 v[14:15], v[2:3], s[100:101]
	v_exp_f32_e32 v8, v8
	v_exp_f32_e32 v9, v9
	v_exp_f32_e32 v10, v10
	v_exp_f32_e32 v11, v11
	v_exp_f32_e32 v12, v12
	v_exp_f32_e32 v13, v13
	v_exp_f32_e32 v14, v14
	v_exp_f32_e32 v15, v15
	v_pk_add_f32 v[8:9], v[8:9], v[252:253]
	v_pk_add_f32 v[10:11], v[10:11], v[252:253]
	v_pk_add_f32 v[12:13], v[12:13], v[252:253]
	v_pk_add_f32 v[14:15], v[14:15], v[252:253]
	v_rcp_f32_e32 v8, v8
	v_rcp_f32_e32 v9, v9
	v_rcp_f32_e32 v10, v10
	v_rcp_f32_e32 v11, v11
	v_rcp_f32_e32 v12, v12
	v_rcp_f32_e32 v13, v13
	v_rcp_f32_e32 v14, v14
	v_rcp_f32_e32 v15, v15
	s_nop 0
	v_cvt_pk_bf16_f32 v8, v8, v9
	v_cvt_pk_bf16_f32 v9, v10, v11
	v_cvt_pk_bf16_f32 v10, v12, v13
	v_cvt_pk_bf16_f32 v11, v14, v15
	global_store_dwordx4 v174, v[8:11], s[60:61] offset:256
	s_branch .Lwin_done
